# ln_router both layers: first token's row loads issued before the router-weight LDS fill
# baseline (speedup 1.0000x reference)
.LBB0_830:
	s_or_b64 exec, exec, s[0:1]
	v_mov_b32_e32 v2, v250
	s_movk_i32 s0, 0x1000
	s_waitcnt lgkmcnt(0)
	s_barrier
	v_readlane_b32 s98, v255, 0
	v_readlane_b32 s99, v255, 1
	v_ashrrev_i32_e32 v232, 6, v250
	v_mov_b32_e32 v233, s55
	v_lshl_add_u32 v232, v233, 2, v232
	v_lshlrev_b32_e32 v232, 12, v232
	v_and_b32_e32 v233, 63, v250
	v_lshl_add_u32 v232, v233, 4, v232
	global_load_dwordx4 v[28:31], v232, s[98:99]
	global_load_dwordx4 v[24:27], v232, s[98:99] offset:1024
	global_load_dwordx4 v[20:23], v232, s[98:99] offset:2048
	global_load_dwordx4 v[16:19], v232, s[98:99] offset:3072
	s_nop 0
	v_cmp_gt_i32_e32 vcc, s0, v2
	s_and_saveexec_b64 s[0:1], vcc
	v_readlane_b32 s4, v253, 26
	v_readlane_b32 s8, v253, 30
	v_readlane_b32 s9, v253, 31
	v_readlane_b32 s5, v253, 27
	v_readlane_b32 s6, v253, 28
	v_readlane_b32 s7, v253, 29
	v_readlane_b32 s10, v253, 32
	v_readlane_b32 s11, v253, 33
	v_readlane_b32 s12, v253, 34
	v_readlane_b32 s13, v253, 35
	v_readlane_b32 s14, v253, 36
	v_readlane_b32 s15, v253, 37
	v_readlane_b32 s16, v253, 38
	v_readlane_b32 s17, v253, 39
	v_readlane_b32 s18, v253, 40
	v_readlane_b32 s19, v253, 41
	s_cbranch_execz .LBB0_833
	v_add_u32_e32 v3, 0xffffff00, v2
	v_lshlrev_b32_e32 v4, 4, v2
	s_waitcnt vmcnt(7)
	v_lshlrev_b32_e32 v0, 2, v2
	s_mov_b64 s[2:3], 0
	s_movk_i32 s4, 0xeff

.LBB0_833:
	s_or_b64 exec, exec, s[0:1]
	s_waitcnt vmcnt(3)
	v_ashrrev_i32_e32 v0, 6, v2
	s_lshl_b32 s96, s55, 2
	v_add_u32_e32 v48, s96, v0
	s_movk_i32 s10, 0x2000
	v_cmp_gt_i32_e32 vcc, s10, v48
	s_waitcnt lgkmcnt(0)
	s_barrier
	s_and_saveexec_b64 s[36:37], vcc
	s_cbranch_execz .LBB0_842
	v_readlane_b32 s12, v253, 50
	v_readlane_b32 s13, v253, 51
	v_readlane_b32 s14, v253, 52
	v_readlane_b32 s15, v253, 53
	v_readlane_b32 s24, v253, 62
	v_readlane_b32 s25, v253, 63
	v_ashrrev_i32_e32 v49, 31, v48
	v_readlane_b32 s26, v255, 0
	v_readlane_b32 s27, v255, 1
	s_mov_b64 s[12:13], s[24:25]
	v_and_b32_e32 v50, 63, v2
	v_lshlrev_b64 v[0:1], 12, v[48:49]
	s_mov_b64 s[14:15], s[26:27]
	v_mov_b32_e32 v51, 0
	v_lshl_add_u64 v[4:5], s[14:15], 0, v[0:1]
	v_lshlrev_b32_e32 v52, 4, v50
	v_mov_b32_e32 v53, v51
	v_lshl_add_u64 v[4:5], v[4:5], 0, v[52:53]
	v_and_b32_e32 v1, 32, v2
	v_cmp_eq_u32_e64 s[34:35], 0, v1
	v_and_b32_e32 v1, 16, v2
	v_cmp_eq_u32_e64 s[4:5], 0, v1
	v_and_b32_e32 v1, 8, v2
	v_cmp_eq_u32_e64 s[6:7], 0, v1
	v_and_b32_e32 v1, 4, v2
	v_cmp_eq_u32_e64 s[8:9], 0, v1
	v_mbcnt_lo_u32_b32 v1, -1, 0
	v_mbcnt_hi_u32_b32 v1, -1, v1
	v_and_b32_e32 v4, 64, v1
	v_xor_b32_e32 v3, 8, v1
	v_add_u32_e32 v4, 64, v4
	v_cmp_lt_i32_e32 vcc, v3, v4
	v_readlane_b32 s16, v253, 54
	v_readlane_b32 s17, v253, 55
	v_cndmask_b32_e32 v3, v1, v3, vcc
	v_lshlrev_b32_e32 v77, 2, v3
	v_xor_b32_e32 v3, 4, v1
	v_cmp_lt_i32_e32 vcc, v3, v4
	v_readlane_b32 s18, v253, 56
	v_readlane_b32 s19, v253, 57
	v_cndmask_b32_e32 v3, v1, v3, vcc
	v_lshlrev_b32_e32 v84, 2, v3
	v_xor_b32_e32 v3, 2, v1
	v_cmp_lt_i32_e32 vcc, v3, v4
	v_readlane_b32 s20, v253, 58
	v_readlane_b32 s21, v253, 59
	v_cndmask_b32_e32 v3, v1, v3, vcc
	v_lshlrev_b32_e32 v85, 2, v3
	v_xor_b32_e32 v3, 1, v1
	v_readlane_b32 s22, v253, 60
	v_readlane_b32 s23, v253, 61
	v_cmp_lt_i32_e32 vcc, v3, v4
	v_lshlrev_b32_e32 v0, 2, v50
	v_readlane_b32 s16, v254, 18
	v_cndmask_b32_e32 v1, v1, v3, vcc
	v_readlane_b32 s76, v253, 26
	v_lshlrev_b32_e32 v86, 2, v1
	v_and_b32_e32 v1, 3, v2
	v_cmp_eq_u32_e64 s[12:13], 1, v50
	v_readlane_b32 s22, v254, 24
	v_readlane_b32 s23, v254, 25
	v_readlane_b32 s24, v254, 26
	v_readlane_b32 s25, v254, 27
	v_or_b32_e32 v2, 0x100, v0
	v_or_b32_e32 v4, 0x200, v0
	v_or_b32_e32 v6, 0x300, v0
	v_lshl_add_u64 v[60:61], s[66:67], 0, v[50:51]
	v_lshlrev_b32_e32 v50, 3, v50
	v_readlane_b32 s77, v253, 27
	s_lshl_b32 s11, s92, 2
	v_cmp_eq_u32_e64 s[0:1], 0, v1
	v_lshl_add_u64 v[54:55], s[22:23], 0, v[52:53]
	v_lshl_add_u64 v[56:57], s[24:25], 0, v[52:53]
	v_lshl_add_u64 v[58:59], s[14:15], 0, v[52:53]
	v_lshl_add_u64 v[62:63], s[64:65], 0, v[50:51]
	s_mov_b64 s[22:23], 0
	v_mov_b64_e32 v[64:65], s[76:77]
	v_lshlrev_b32_e32 v50, 2, v0
	v_lshlrev_b32_e32 v66, 2, v2
	v_mov_b32_e32 v67, v51
	v_lshlrev_b32_e32 v68, 2, v4
	v_mov_b32_e32 v69, v51
	v_lshlrev_b32_e32 v70, 2, v6
	v_mov_b32_e32 v71, v51
	v_mov_b32_e32 v53, 0x7f800000
	v_readlane_b32 s17, v254, 19
	v_readlane_b32 s18, v254, 20
	v_readlane_b32 s19, v254, 21
	v_readlane_b32 s20, v254, 22
	v_readlane_b32 s21, v254, 23
	v_readlane_b32 s26, v254, 28
	v_readlane_b32 s27, v254, 29
	v_readlane_b32 s28, v254, 30
	v_readlane_b32 s29, v254, 31
	s_waitcnt vmcnt(3)
	v_mov_b64_e32 v[0:1], v[28:29]
	v_mov_b64_e32 v[2:3], v[30:31]
	s_waitcnt vmcnt(2)
	v_mov_b64_e32 v[4:5], v[24:25]
	v_mov_b64_e32 v[6:7], v[26:27]
	s_waitcnt vmcnt(1)
	v_mov_b64_e32 v[8:9], v[20:21]
	v_mov_b64_e32 v[10:11], v[22:23]
	s_waitcnt vmcnt(0)
	v_mov_b64_e32 v[12:13], v[16:17]
	v_mov_b64_e32 v[14:15], v[18:19]
	v_readlane_b32 s30, v254, 32
	v_readlane_b32 s31, v254, 33
	v_readlane_b32 s78, v253, 28
	v_readlane_b32 s79, v253, 29
	v_readlane_b32 s80, v253, 30
	v_readlane_b32 s81, v253, 31
	v_readlane_b32 s82, v253, 32
	v_readlane_b32 s83, v253, 33
	v_readlane_b32 s84, v253, 34
	v_readlane_b32 s85, v253, 35
	v_readlane_b32 s86, v253, 36
	v_readlane_b32 s87, v253, 37
	v_readlane_b32 s88, v253, 38
	v_readlane_b32 s89, v253, 39
	v_readlane_b32 s90, v253, 40
	v_readlane_b32 s91, v253, 41
	s_branch .LBB0_836

.LBB0_1863:
	s_or_b64 exec, exec, s[0:1]
	v_mov_b32_e32 v2, v250
	s_movk_i32 s0, 0x1000
	s_waitcnt lgkmcnt(0)
	s_barrier
	v_readlane_b32 s98, v255, 0
	v_readlane_b32 s99, v255, 1
	v_ashrrev_i32_e32 v232, 6, v250
	v_add_u32_e32 v232, s96, v232
	v_lshlrev_b32_e32 v232, 12, v232
	v_and_b32_e32 v233, 63, v250
	v_lshl_add_u32 v232, v233, 4, v232
	global_load_dwordx4 v[28:31], v232, s[98:99]
	global_load_dwordx4 v[24:27], v232, s[98:99] offset:1024
	global_load_dwordx4 v[20:23], v232, s[98:99] offset:2048
	global_load_dwordx4 v[16:19], v232, s[98:99] offset:3072
	s_nop 0
	v_cmp_gt_i32_e32 vcc, s0, v2
	s_and_saveexec_b64 s[0:1], vcc
	s_cbranch_execz .LBB0_1866
	v_readlane_b32 s4, v253, 26
	v_readlane_b32 s8, v253, 30
	v_readlane_b32 s5, v253, 27
	v_readlane_b32 s6, v253, 28
	v_readlane_b32 s9, v253, 31
	s_add_u32 s2, s8, 0x10000
	s_addc_u32 s3, s9, 0
	v_add_u32_e32 v3, 0xffffff00, v2
	s_waitcnt vmcnt(4)
	v_lshlrev_b32_e32 v4, 4, v2
	v_lshlrev_b32_e32 v0, 2, v2
	s_mov_b64 s[4:5], 0
	s_movk_i32 s6, 0xeff
	v_readlane_b32 s7, v253, 29
	v_readlane_b32 s10, v253, 32
	v_readlane_b32 s11, v253, 33
	v_readlane_b32 s12, v253, 34
	v_readlane_b32 s13, v253, 35
	v_readlane_b32 s14, v253, 36
	v_readlane_b32 s15, v253, 37
	v_readlane_b32 s16, v253, 38
	v_readlane_b32 s17, v253, 39
	v_readlane_b32 s18, v253, 40
	v_readlane_b32 s19, v253, 41

.LBB0_1866:
	s_or_b64 exec, exec, s[0:1]
	v_ashrrev_i32_e32 v0, 6, v2
	s_waitcnt vmcnt(0)
	v_add_u32_e32 v32, s96, v0
	s_movk_i32 s25, 0x2000
	v_cmp_gt_i32_e32 vcc, s25, v32
	s_waitcnt lgkmcnt(0)
	s_barrier
	s_and_saveexec_b64 s[20:21], vcc
	v_readlane_b32 s4, v254, 18
	v_readlane_b32 s5, v254, 19
	v_readlane_b32 s6, v254, 20
	v_readlane_b32 s7, v254, 21
	v_readlane_b32 s8, v254, 22
	v_readlane_b32 s9, v254, 23
	v_readlane_b32 s10, v254, 24
	v_readlane_b32 s11, v254, 25
	v_readlane_b32 s12, v254, 26
	v_readlane_b32 s13, v254, 27
	v_readlane_b32 s14, v254, 28
	v_readlane_b32 s15, v254, 29
	v_readlane_b32 s16, v254, 30
	v_readlane_b32 s17, v254, 31
	v_readlane_b32 s18, v254, 32
	v_readlane_b32 s19, v254, 33
	s_cbranch_execz .LBB0_1875
	v_readlane_b32 s0, v254, 18
	v_readlane_b32 s76, v253, 50
	v_readlane_b32 s14, v254, 32
	v_readlane_b32 s15, v254, 33
	v_ashrrev_i32_e32 v33, 31, v32
	v_readlane_b32 s90, v255, 0
	v_readlane_b32 s91, v255, 1
	v_and_b32_e32 v34, 63, v2
	v_lshlrev_b64 v[0:1], 12, v[32:33]
	s_mov_b64 s[14:15], s[90:91]
	v_mov_b32_e32 v35, 0
	v_lshl_add_u64 v[0:1], s[14:15], 0, v[0:1]
	v_lshlrev_b32_e32 v36, 4, v34
	v_mov_b32_e32 v37, v35
	v_lshl_add_u64 v[0:1], v[0:1], 0, v[36:37]
	v_readlane_b32 s1, v254, 19
	v_readlane_b32 s2, v254, 20
	v_readlane_b32 s8, v254, 26
	v_and_b32_e32 v0, 32, v2
	v_readlane_b32 s3, v254, 21
	v_readlane_b32 s9, v254, 27
	s_add_u32 s2, s8, 0x2000
	v_cmp_eq_u32_e64 s[0:1], 0, v0
	v_and_b32_e32 v0, 16, v2
	v_readlane_b32 s4, v254, 22
	v_readlane_b32 s5, v254, 23
	v_readlane_b32 s6, v254, 24
	v_readlane_b32 s10, v254, 28
	s_addc_u32 s3, s9, 0
	v_cmp_eq_u32_e64 s[16:17], 0, v0
	v_and_b32_e32 v0, 8, v2
	v_readlane_b32 s7, v254, 25
	v_readlane_b32 s11, v254, 29
	s_add_u32 s10, s6, 0x2000
	v_cmp_eq_u32_e64 s[4:5], 0, v0
	v_and_b32_e32 v0, 4, v2
	s_addc_u32 s11, s7, 0
	v_cmp_eq_u32_e64 s[6:7], 0, v0
	v_mbcnt_lo_u32_b32 v0, -1, 0
	v_mbcnt_hi_u32_b32 v0, -1, v0
	v_and_b32_e32 v3, 64, v0
	v_xor_b32_e32 v1, 8, v0
	v_add_u32_e32 v3, 64, v3
	v_cmp_lt_i32_e32 vcc, v1, v3
	v_lshlrev_b32_e32 v4, 2, v34
	v_readlane_b32 s77, v253, 51
	v_cndmask_b32_e32 v1, v0, v1, vcc
	v_lshlrev_b32_e32 v70, 2, v1
	v_xor_b32_e32 v1, 4, v0
	v_cmp_lt_i32_e32 vcc, v1, v3
	v_readlane_b32 s78, v253, 52
	v_readlane_b32 s79, v253, 53
	v_cndmask_b32_e32 v1, v0, v1, vcc
	v_lshlrev_b32_e32 v71, 2, v1
	v_xor_b32_e32 v1, 2, v0
	v_cmp_lt_i32_e32 vcc, v1, v3
	v_readlane_b32 s80, v253, 54
	v_readlane_b32 s81, v253, 55
	v_cndmask_b32_e32 v1, v0, v1, vcc
	v_lshlrev_b32_e32 v72, 2, v1
	v_xor_b32_e32 v1, 1, v0
	v_cmp_lt_i32_e32 vcc, v1, v3
	v_mov_b32_e32 v3, v35
	v_readlane_b32 s82, v253, 56
	v_cndmask_b32_e32 v0, v0, v1, vcc
	v_lshlrev_b32_e32 v73, 2, v0
	v_and_b32_e32 v0, 3, v2
	v_cmp_eq_u32_e64 s[8:9], 0, v0
	v_or_b32_e32 v0, 0x100, v4
	v_lshlrev_b32_e32 v2, 2, v0
	v_lshl_add_u64 v[42:43], s[10:11], 0, v[2:3]
	v_lshl_add_u64 v[44:45], s[2:3], 0, v[2:3]
	v_or_b32_e32 v2, 0x200, v4
	v_readlane_b32 s83, v253, 57
	v_readlane_b32 s84, v253, 58
	v_readlane_b32 s85, v253, 59
	v_readlane_b32 s86, v253, 60
	v_readlane_b32 s87, v253, 61
	v_readlane_b32 s88, v253, 62
	v_readlane_b32 s89, v253, 63
	v_lshlrev_b32_e32 v6, 2, v2
	v_mov_b32_e32 v7, v35
	v_readlane_b32 s12, v254, 30
	v_readlane_b32 s13, v254, 31
	v_lshl_add_u64 v[46:47], s[10:11], 0, v[6:7]
	v_lshl_add_u64 v[48:49], s[2:3], 0, v[6:7]
	v_or_b32_e32 v6, 0x300, v4
	v_readlane_b32 s76, v253, 26
	v_cmp_eq_u32_e64 s[12:13], 1, v34
	v_lshlrev_b32_e32 v8, 2, v6
	v_mov_b32_e32 v9, v35
	v_lshl_add_u64 v[56:57], s[66:67], 0, v[34:35]
	v_lshlrev_b32_e32 v34, 3, v34
	v_readlane_b32 s77, v253, 27
	s_lshl_b32 s30, s92, 2
	v_lshl_add_u64 v[38:39], s[10:11], 0, v[36:37]
	v_lshl_add_u64 v[40:41], s[2:3], 0, v[36:37]
	v_lshl_add_u64 v[50:51], s[10:11], 0, v[8:9]
	v_lshl_add_u64 v[52:53], s[2:3], 0, v[8:9]
	v_lshl_add_u64 v[54:55], s[14:15], 0, v[36:37]
	v_lshl_add_u64 v[58:59], s[64:65], 0, v[34:35]
	s_mov_b64 s[22:23], 0
	s_movk_i32 s10, 0xfff
	s_movk_i32 s11, 0x1fff
	s_movk_i32 s31, 0x6000
	v_mov_b64_e32 v[60:61], s[76:77]
	s_mov_b32 s24, 0x3a800000
	s_mov_b32 s33, 0x800000
	s_mov_b64 s[26:27], 0x3000
	s_mov_b64 s[28:29], 0x4000
	v_lshlrev_b32_e32 v34, 2, v4
	v_lshlrev_b32_e32 v62, 2, v0
	v_mov_b32_e32 v63, v35
	v_lshlrev_b32_e32 v64, 2, v2
	v_mov_b32_e32 v65, v35
	v_lshlrev_b32_e32 v66, 2, v6
	v_mov_b32_e32 v67, v35
	s_mov_b32 s34, 0x3fb8aa3b
	s_mov_b32 s35, 0xc2ce8ed0
	s_mov_b32 s36, 0x42b17218
	v_mov_b32_e32 v37, 0x7f800000
	s_waitcnt vmcnt(3)
	v_mov_b64_e32 v[0:1], v[28:29]
	v_mov_b64_e32 v[2:3], v[30:31]
	s_waitcnt vmcnt(2)
	v_mov_b64_e32 v[4:5], v[24:25]
	v_mov_b64_e32 v[6:7], v[26:27]
	s_waitcnt vmcnt(1)
	v_mov_b64_e32 v[8:9], v[20:21]
	v_mov_b64_e32 v[10:11], v[22:23]
	s_waitcnt vmcnt(0)
	v_mov_b64_e32 v[12:13], v[16:17]
	v_mov_b64_e32 v[14:15], v[18:19]
	v_readlane_b32 s78, v253, 28
	v_readlane_b32 s79, v253, 29
	v_readlane_b32 s80, v253, 30
	v_readlane_b32 s81, v253, 31
	v_readlane_b32 s82, v253, 32
	v_readlane_b32 s83, v253, 33
	v_readlane_b32 s84, v253, 34
	v_readlane_b32 s85, v253, 35
	v_readlane_b32 s86, v253, 36
	v_readlane_b32 s87, v253, 37
	v_readlane_b32 s88, v253, 38
	v_readlane_b32 s89, v253, 39
	v_readlane_b32 s90, v253, 40
	v_readlane_b32 s91, v253, 41
	s_branch .LBB0_1869
